# v066 plus first-K-tile LDS fragment reads of each QKV and FFN-in tile hoisted above the tile-scheduling scalar block
# baseline (speedup 1.0000x reference)
.LBB0_488:
	v_add_u32_e32 v156, 0x10000, v141
	v_add_u32_e32 v172, 0x14000, v141
	ds_read_b128 v[144:147], v156
	ds_read_b128 v[148:151], v156 offset:1024
	ds_read_b128 v[152:155], v156 offset:2048
	ds_read_b128 v[156:159], v156 offset:3072
	ds_read_b128 v[160:163], v172
	ds_read_b128 v[164:167], v172 offset:1024
	ds_read_b128 v[168:171], v172 offset:2048
	ds_read_b128 v[172:175], v172 offset:3072
	ds_read_b128 v[176:179], v143
	ds_read_b128 v[180:183], v143 offset:1024
	ds_read_b128 v[184:187], v143 offset:2048
	ds_read_b128 v[188:191], v143 offset:3072
	ds_read_b128 v[192:195], v143 offset:4096
	ds_read_b128 v[196:199], v143 offset:5120
	ds_read_b128 v[200:203], v143 offset:6144
	ds_read_b128 v[204:207], v143 offset:7168
	s_add_i32 s48, s48, 1
	s_mul_i32 s9, s48, s47
	s_mul_hi_u32 s11, s48, s23
	s_add_i32 s11, s11, s9
	s_mul_i32 s9, s48, s23
	s_add_u32 s12, s9, s24
	s_addc_u32 s13, s11, s38
	v_mov_b64_e32 v[2:3], 0x660
	v_cmp_lt_i64_e64 s[34:35], s[12:13], v[2:3]
	v_mov_b64_e32 v[2:3], 0x65f
	v_cmp_gt_i64_e32 vcc, s[12:13], v[2:3]
	s_cbranch_vccnz .LBB0_490
	s_ashr_i32 s8, s12, 31
	s_lshr_b32 s8, s8, 29
	s_add_i32 s8, s12, s8
	s_ashr_i32 s9, s8, 3
	s_and_b32 s8, s8, -8
	s_sub_i32 s8, s12, s8
	s_cmp_lt_i32 s8, 0
	s_movk_i32 s10, 0xcd
	s_cselect_b32 s10, s10, 0xcc
	s_mul_i32 s8, s8, s10
	s_add_i32 s8, s8, s9
	s_mul_hi_i32 s9, s8, 0x2aaaaaab
	s_lshr_b32 s10, s9, 31
	s_ashr_i32 s9, s9, 5
	s_add_i32 s9, s9, s10
	s_lshl_b32 s10, s9, 3
	s_sub_i32 s11, 0x44, s10
	s_min_i32 s11, s11, 8
	s_abs_i32 s12, s11
	v_cvt_f32_u32_e32 v2, s12
	s_sub_i32 s14, 0, s12
	s_mulk_i32 s9, 0xc0
	s_sub_i32 s9, s8, s9
	v_rcp_iflag_f32_e32 v2, v2
	s_abs_i32 s8, s9
	s_xor_b32 s13, s9, s11
	s_ashr_i32 s13, s13, 31
	v_mul_f32_e32 v2, 0x4f7ffffe, v2
	v_cvt_u32_f32_e32 v2, v2
	s_nop 0
	v_readfirstlane_b32 s15, v2
	s_mul_i32 s14, s14, s15
	s_mul_hi_u32 s14, s15, s14
	s_add_i32 s15, s15, s14
	s_mul_hi_u32 s14, s8, s15
	s_mul_i32 s15, s14, s12
	s_sub_i32 s8, s8, s15
	s_add_i32 s20, s14, 1
	s_sub_i32 s15, s8, s12
	s_cmp_ge_u32 s8, s12
	s_cselect_b32 s14, s20, s14
	s_cselect_b32 s8, s15, s8
	s_add_i32 s15, s14, 1
	s_cmp_ge_u32 s8, s12
	s_cselect_b32 s8, s15, s14
	s_xor_b32 s8, s8, s13
	s_sub_i32 s8, s8, s13
	s_mul_i32 s11, s8, s11
	s_sub_i32 s9, s9, s11
	s_add_i32 s10, s10, s9
.LBB0_490:
	s_ashr_i32 s11, s10, 31
	s_lshl_b64 s[12:13], s[10:11], 20
	v_readlane_b32 s14, v253, 25
	v_readlane_b32 s15, v253, 26
	s_add_u32 s12, s14, s12
	s_addc_u32 s13, s15, s13
	s_and_b64 s[14:15], s[34:35], exec
	s_cselect_b32 s11, s13, s17
	s_cselect_b32 s49, s12, s16
	s_ashr_i32 s9, s8, 31
	s_lshl_b64 s[14:15], s[8:9], 20
	s_add_u32 s14, s25, s14
	s_addc_u32 s15, s36, s15
	s_and_b64 s[20:21], s[34:35], exec
	s_cselect_b32 s9, s15, s19
	s_cselect_b32 s50, s14, s18
	s_add_u32 s16, s16, 0x80080
	s_addc_u32 s17, s17, 0
	s_add_u32 s51, s18, 0x100
	s_addc_u32 s52, s19, 0
	s_mov_b32 s53, -2
	s_add_u32 s18, s16, 0xfff80080
	s_addc_u32 s19, s17, -1
	s_add_i32 s54, 0, 0x10000
	s_cmp_eq_u32 s53, 28
	s_cselect_b32 s21, s11, s19
	s_cselect_b32 s20, s49, s18
	s_cselect_b32 s19, s9, s52
	s_cselect_b32 s18, s50, s51
	s_add_i32 s56, 0, 0x14000
	v_lshl_add_u64 v[208:209], s[16:17], 0, v[136:137]
	s_add_i32 m0, s39, 0xc000
	global_load_lds_dwordx4 v[208:209], off
	v_lshl_add_u64 v[208:209], s[16:17], 0, v[138:139]
	s_add_i32 m0, s39, 0xe000
	s_nop 0
	global_load_lds_dwordx4 v[208:209], off
	s_waitcnt vmcnt(8)
	s_waitcnt lgkmcnt(0)
	s_setprio 1
	s_barrier
	v_mfma_f32_16x16x32_bf16 v[126:129], v[144:147], v[176:179], 0
	v_mfma_f32_16x16x32_bf16 v[122:125], v[152:155], v[176:179], 0
	v_mfma_f32_16x16x32_bf16 v[118:121], v[144:147], v[184:187], 0
	v_mfma_f32_16x16x32_bf16 v[114:117], v[152:155], v[184:187], 0
	v_mfma_f32_16x16x32_bf16 v[102:105], v[144:147], v[192:195], 0
	v_mfma_f32_16x16x32_bf16 v[98:101], v[152:155], v[192:195], 0
	v_mfma_f32_16x16x32_bf16 v[86:89], v[144:147], v[200:203], 0
	v_mfma_f32_16x16x32_bf16 v[82:85], v[152:155], v[200:203], 0
	v_mfma_f32_16x16x32_bf16 v[126:129], v[148:151], v[180:183], v[126:129]
	v_mfma_f32_16x16x32_bf16 v[122:125], v[156:159], v[180:183], v[122:125]
	v_mfma_f32_16x16x32_bf16 v[118:121], v[148:151], v[188:191], v[118:121]
	v_mfma_f32_16x16x32_bf16 v[114:117], v[156:159], v[188:191], v[114:117]
	v_mfma_f32_16x16x32_bf16 v[102:105], v[148:151], v[196:199], v[102:105]
	v_mfma_f32_16x16x32_bf16 v[98:101], v[156:159], v[196:199], v[98:101]
	v_mfma_f32_16x16x32_bf16 v[86:89], v[148:151], v[204:207], v[86:89]
	v_mfma_f32_16x16x32_bf16 v[82:85], v[156:159], v[204:207], v[82:85]
	s_setprio 0
	s_setprio 1
	v_mfma_f32_16x16x32_bf16 v[110:113], v[160:163], v[176:179], 0
	v_mfma_f32_16x16x32_bf16 v[106:109], v[168:171], v[176:179], 0
	v_mfma_f32_16x16x32_bf16 v[94:97], v[160:163], v[184:187], 0
	v_mfma_f32_16x16x32_bf16 v[90:93], v[168:171], v[184:187], 0
	v_mfma_f32_16x16x32_bf16 v[78:81], v[160:163], v[192:195], 0
	v_mfma_f32_16x16x32_bf16 v[74:77], v[168:171], v[192:195], 0
	v_mfma_f32_16x16x32_bf16 v[70:73], v[160:163], v[200:203], 0
	v_mfma_f32_16x16x32_bf16 v[66:69], v[168:171], v[200:203], 0
	v_mfma_f32_16x16x32_bf16 v[110:113], v[164:167], v[180:183], v[110:113]
	v_mfma_f32_16x16x32_bf16 v[106:109], v[172:175], v[180:183], v[106:109]
	v_mfma_f32_16x16x32_bf16 v[94:97], v[164:167], v[188:191], v[94:97]
	v_mfma_f32_16x16x32_bf16 v[90:93], v[172:175], v[188:191], v[90:93]
	v_mfma_f32_16x16x32_bf16 v[78:81], v[164:167], v[196:199], v[78:81]
	v_mfma_f32_16x16x32_bf16 v[74:77], v[172:175], v[196:199], v[74:77]
	v_mfma_f32_16x16x32_bf16 v[70:73], v[164:167], v[204:207], v[70:73]
	v_mfma_f32_16x16x32_bf16 v[66:69], v[172:175], v[204:207], v[66:69]
	s_barrier
	s_setprio 0
	s_add_i32 s54, s54, s37
	v_lshl_add_u64 v[208:209], s[18:19], 0, v[0:1]
	s_mov_b32 m0, s54
	ds_read_b128 v[176:179], v143 offset:16384
	ds_read_b128 v[180:183], v143 offset:17408
	ds_read_b128 v[184:187], v143 offset:18432
	ds_read_b128 v[188:191], v143 offset:19456
	ds_read_b128 v[192:195], v143 offset:20480
	ds_read_b128 v[196:199], v143 offset:21504
	ds_read_b128 v[200:203], v143 offset:22528
	ds_read_b128 v[204:207], v143 offset:23552
	global_load_lds_dwordx4 v[208:209], off
	s_add_i32 m0, s54, 0x2000
	s_add_u32 s54, s18, 0x80000
	v_lshl_add_u64 v[220:221], s[18:19], 0, v[130:131]
	s_addc_u32 s55, s19, 0
	s_add_i32 s56, s56, s37
	global_load_lds_dwordx4 v[220:221], off
	v_lshl_add_u64 v[222:223], s[54:55], 0, v[0:1]
	s_mov_b32 m0, s56
	v_lshl_add_u64 v[224:225], s[20:21], 0, v[132:133]
	global_load_lds_dwordx4 v[222:223], off
	v_lshl_add_u64 v[222:223], s[54:55], 0, v[130:131]
	s_add_i32 m0, s56, 0x2000
	s_nop 0
	global_load_lds_dwordx4 v[222:223], off
	v_lshl_add_u64 v[222:223], s[20:21], 0, v[134:135]
	s_mov_b32 m0, s39
	s_nop 0
	global_load_lds_dwordx4 v[222:223], off
	s_mov_b32 m0, s40
	s_nop 0
	global_load_lds_dwordx4 v[224:225], off
	s_waitcnt vmcnt(8)
	s_waitcnt lgkmcnt(0)
	s_setprio 1
	s_barrier
	v_mfma_f32_16x16x32_bf16 v[62:65], v[144:147], v[176:179], 0
	v_mfma_f32_16x16x32_bf16 v[58:61], v[152:155], v[176:179], 0
	v_mfma_f32_16x16x32_bf16 v[54:57], v[144:147], v[184:187], 0
	v_mfma_f32_16x16x32_bf16 v[50:53], v[152:155], v[184:187], 0
	v_mfma_f32_16x16x32_bf16 v[38:41], v[144:147], v[192:195], 0
	v_mfma_f32_16x16x32_bf16 v[34:37], v[152:155], v[192:195], 0
	v_mfma_f32_16x16x32_bf16 v[22:25], v[144:147], v[200:203], 0
	v_mfma_f32_16x16x32_bf16 v[18:21], v[152:155], v[200:203], 0
	v_mfma_f32_16x16x32_bf16 v[62:65], v[148:151], v[180:183], v[62:65]
	v_mfma_f32_16x16x32_bf16 v[58:61], v[156:159], v[180:183], v[58:61]
	v_mfma_f32_16x16x32_bf16 v[54:57], v[148:151], v[188:191], v[54:57]
	v_mfma_f32_16x16x32_bf16 v[50:53], v[156:159], v[188:191], v[50:53]
	v_mfma_f32_16x16x32_bf16 v[38:41], v[148:151], v[196:199], v[38:41]
	v_mfma_f32_16x16x32_bf16 v[34:37], v[156:159], v[196:199], v[34:37]
	v_mfma_f32_16x16x32_bf16 v[22:25], v[148:151], v[204:207], v[22:25]
	v_mfma_f32_16x16x32_bf16 v[18:21], v[156:159], v[204:207], v[18:21]
	s_setprio 0
	s_setprio 1
	v_mfma_f32_16x16x32_bf16 v[46:49], v[160:163], v[176:179], 0
	v_mfma_f32_16x16x32_bf16 v[42:45], v[168:171], v[176:179], 0
	v_mfma_f32_16x16x32_bf16 v[30:33], v[160:163], v[184:187], 0
	v_mfma_f32_16x16x32_bf16 v[26:29], v[168:171], v[184:187], 0
	v_mfma_f32_16x16x32_bf16 v[14:17], v[160:163], v[192:195], 0
	v_mfma_f32_16x16x32_bf16 v[10:13], v[168:171], v[192:195], 0
	v_mfma_f32_16x16x32_bf16 v[6:9], v[160:163], v[200:203], 0
	v_mfma_f32_16x16x32_bf16 v[2:5], v[168:171], v[200:203], 0
	v_mfma_f32_16x16x32_bf16 v[46:49], v[164:167], v[180:183], v[46:49]
	v_mfma_f32_16x16x32_bf16 v[42:45], v[172:175], v[180:183], v[42:45]
	v_mfma_f32_16x16x32_bf16 v[30:33], v[164:167], v[188:191], v[30:33]
	v_mfma_f32_16x16x32_bf16 v[26:29], v[172:175], v[188:191], v[26:29]
	v_mfma_f32_16x16x32_bf16 v[14:17], v[164:167], v[196:199], v[14:17]
	v_mfma_f32_16x16x32_bf16 v[10:13], v[172:175], v[196:199], v[10:13]
	v_mfma_f32_16x16x32_bf16 v[6:9], v[164:167], v[204:207], v[6:9]
	v_mfma_f32_16x16x32_bf16 v[2:5], v[172:175], v[204:207], v[2:5]
	s_barrier
	s_setprio 0
	s_add_i32 s54, 0, 0x18000
	s_add_i32 s55, 0, 0x1c000
	v_add_u32_e32 v156, s54, v141
	v_add_u32_e32 v172, s55, v141
	ds_read_b128 v[144:147], v156
	ds_read_b128 v[148:151], v156 offset:1024
	ds_read_b128 v[152:155], v156 offset:2048
	ds_read_b128 v[156:159], v156 offset:3072
	ds_read_b128 v[160:163], v172
	ds_read_b128 v[164:167], v172 offset:1024
	ds_read_b128 v[168:171], v172 offset:2048
	ds_read_b128 v[172:175], v172 offset:3072
	s_add_u32 s20, s20, 0x80000
	s_addc_u32 s21, s21, 0
	s_mov_b32 m0, s41
	v_lshl_add_u64 v[226:227], s[20:21], 0, v[134:135]
	ds_read_b128 v[176:179], v143 offset:32768
	ds_read_b128 v[180:183], v143 offset:33792
	ds_read_b128 v[184:187], v143 offset:34816
	ds_read_b128 v[188:191], v143 offset:35840
	ds_read_b128 v[192:195], v143 offset:36864
	ds_read_b128 v[196:199], v143 offset:37888
	ds_read_b128 v[200:203], v143 offset:38912
	ds_read_b128 v[204:207], v143 offset:39936
	global_load_lds_dwordx4 v[226:227], off
	v_lshl_add_u64 v[226:227], s[20:21], 0, v[132:133]
	s_mov_b32 m0, s44
	s_nop 0
	global_load_lds_dwordx4 v[226:227], off
	s_waitcnt vmcnt(8)
	s_waitcnt lgkmcnt(0)
	s_setprio 1
	s_barrier
	v_mfma_f32_16x16x32_bf16 v[126:129], v[144:147], v[176:179], v[126:129]
	v_mfma_f32_16x16x32_bf16 v[122:125], v[152:155], v[176:179], v[122:125]
	v_mfma_f32_16x16x32_bf16 v[118:121], v[144:147], v[184:187], v[118:121]
	v_mfma_f32_16x16x32_bf16 v[114:117], v[152:155], v[184:187], v[114:117]
	v_mfma_f32_16x16x32_bf16 v[102:105], v[144:147], v[192:195], v[102:105]
	v_mfma_f32_16x16x32_bf16 v[98:101], v[152:155], v[192:195], v[98:101]
	v_mfma_f32_16x16x32_bf16 v[86:89], v[144:147], v[200:203], v[86:89]
	v_mfma_f32_16x16x32_bf16 v[82:85], v[152:155], v[200:203], v[82:85]
	v_mfma_f32_16x16x32_bf16 v[126:129], v[148:151], v[180:183], v[126:129]
	v_mfma_f32_16x16x32_bf16 v[122:125], v[156:159], v[180:183], v[122:125]
	v_mfma_f32_16x16x32_bf16 v[118:121], v[148:151], v[188:191], v[118:121]
	v_mfma_f32_16x16x32_bf16 v[114:117], v[156:159], v[188:191], v[114:117]
	v_mfma_f32_16x16x32_bf16 v[102:105], v[148:151], v[196:199], v[102:105]
	v_mfma_f32_16x16x32_bf16 v[98:101], v[156:159], v[196:199], v[98:101]
	v_mfma_f32_16x16x32_bf16 v[86:89], v[148:151], v[204:207], v[86:89]
	v_mfma_f32_16x16x32_bf16 v[82:85], v[156:159], v[204:207], v[82:85]
	s_setprio 0
	s_setprio 1
	v_mfma_f32_16x16x32_bf16 v[110:113], v[160:163], v[176:179], v[110:113]
	v_mfma_f32_16x16x32_bf16 v[106:109], v[168:171], v[176:179], v[106:109]
	v_mfma_f32_16x16x32_bf16 v[94:97], v[160:163], v[184:187], v[94:97]
	v_mfma_f32_16x16x32_bf16 v[90:93], v[168:171], v[184:187], v[90:93]
	v_mfma_f32_16x16x32_bf16 v[78:81], v[160:163], v[192:195], v[78:81]
	v_mfma_f32_16x16x32_bf16 v[74:77], v[168:171], v[192:195], v[74:77]
	v_mfma_f32_16x16x32_bf16 v[70:73], v[160:163], v[200:203], v[70:73]
	v_mfma_f32_16x16x32_bf16 v[66:69], v[168:171], v[200:203], v[66:69]
	v_mfma_f32_16x16x32_bf16 v[110:113], v[164:167], v[180:183], v[110:113]
	v_mfma_f32_16x16x32_bf16 v[106:109], v[172:175], v[180:183], v[106:109]
	v_mfma_f32_16x16x32_bf16 v[94:97], v[164:167], v[188:191], v[94:97]
	v_mfma_f32_16x16x32_bf16 v[90:93], v[172:175], v[188:191], v[90:93]
	v_mfma_f32_16x16x32_bf16 v[78:81], v[164:167], v[196:199], v[78:81]
	v_mfma_f32_16x16x32_bf16 v[74:77], v[172:175], v[196:199], v[74:77]
	v_mfma_f32_16x16x32_bf16 v[70:73], v[164:167], v[204:207], v[70:73]
	v_mfma_f32_16x16x32_bf16 v[66:69], v[172:175], v[204:207], v[66:69]
	s_barrier
	s_setprio 0
	s_add_i32 s20, s54, s37
	v_lshl_add_u64 v[208:209], v[208:209], 0, s[2:3]
	s_mov_b32 m0, s20
	ds_read_b128 v[176:179], v143 offset:49152
	ds_read_b128 v[180:183], v143 offset:50176
	ds_read_b128 v[184:187], v143 offset:51200
	ds_read_b128 v[188:191], v143 offset:52224
	ds_read_b128 v[192:195], v143 offset:53248
	ds_read_b128 v[196:199], v143 offset:54272
	ds_read_b128 v[200:203], v143 offset:55296
	ds_read_b128 v[204:207], v143 offset:56320
	global_load_lds_dwordx4 v[208:209], off
	s_add_i32 m0, s20, 0x2000
	s_add_u32 s18, s18, 0x80080
	v_lshl_add_u64 v[208:209], v[220:221], 0, s[2:3]
	s_addc_u32 s19, s19, 0
	s_add_i32 s20, s55, s37
	global_load_lds_dwordx4 v[208:209], off
	v_lshl_add_u64 v[208:209], s[18:19], 0, v[0:1]
	s_mov_b32 m0, s20
	s_nop 0
	global_load_lds_dwordx4 v[208:209], off
	v_lshl_add_u64 v[208:209], s[18:19], 0, v[130:131]
	s_add_i32 m0, s20, 0x2000
	s_nop 0
	global_load_lds_dwordx4 v[208:209], off
	v_lshl_add_u64 v[208:209], v[222:223], 0, s[2:3]
	s_mov_b32 m0, s45
	s_nop 0
	global_load_lds_dwordx4 v[208:209], off
	v_lshl_add_u64 v[208:209], v[224:225], 0, s[2:3]
	s_mov_b32 m0, s46
	s_nop 0
	global_load_lds_dwordx4 v[208:209], off
	s_waitcnt vmcnt(8)
	s_waitcnt lgkmcnt(0)
	s_setprio 1
	s_barrier
	v_mfma_f32_16x16x32_bf16 v[62:65], v[144:147], v[176:179], v[62:65]
	v_mfma_f32_16x16x32_bf16 v[58:61], v[152:155], v[176:179], v[58:61]
	v_mfma_f32_16x16x32_bf16 v[54:57], v[144:147], v[184:187], v[54:57]
	v_mfma_f32_16x16x32_bf16 v[50:53], v[152:155], v[184:187], v[50:53]
	v_mfma_f32_16x16x32_bf16 v[38:41], v[144:147], v[192:195], v[38:41]
	v_mfma_f32_16x16x32_bf16 v[34:37], v[152:155], v[192:195], v[34:37]
	v_mfma_f32_16x16x32_bf16 v[22:25], v[144:147], v[200:203], v[22:25]
	v_mfma_f32_16x16x32_bf16 v[18:21], v[152:155], v[200:203], v[18:21]
	v_mfma_f32_16x16x32_bf16 v[62:65], v[148:151], v[180:183], v[62:65]
	v_mfma_f32_16x16x32_bf16 v[58:61], v[156:159], v[180:183], v[58:61]
	v_mfma_f32_16x16x32_bf16 v[54:57], v[148:151], v[188:191], v[54:57]
	v_mfma_f32_16x16x32_bf16 v[50:53], v[156:159], v[188:191], v[50:53]
	v_mfma_f32_16x16x32_bf16 v[38:41], v[148:151], v[196:199], v[38:41]
	v_mfma_f32_16x16x32_bf16 v[34:37], v[156:159], v[196:199], v[34:37]
	v_mfma_f32_16x16x32_bf16 v[22:25], v[148:151], v[204:207], v[22:25]
	v_mfma_f32_16x16x32_bf16 v[18:21], v[156:159], v[204:207], v[18:21]
	s_setprio 0
	s_setprio 1
	v_mfma_f32_16x16x32_bf16 v[46:49], v[160:163], v[176:179], v[46:49]
	v_mfma_f32_16x16x32_bf16 v[42:45], v[168:171], v[176:179], v[42:45]
	v_mfma_f32_16x16x32_bf16 v[30:33], v[160:163], v[184:187], v[30:33]
	v_mfma_f32_16x16x32_bf16 v[26:29], v[168:171], v[184:187], v[26:29]
	v_mfma_f32_16x16x32_bf16 v[14:17], v[160:163], v[192:195], v[14:17]
	v_mfma_f32_16x16x32_bf16 v[10:13], v[168:171], v[192:195], v[10:13]
	v_mfma_f32_16x16x32_bf16 v[6:9], v[160:163], v[200:203], v[6:9]
	v_mfma_f32_16x16x32_bf16 v[2:5], v[168:171], v[200:203], v[2:5]
	v_mfma_f32_16x16x32_bf16 v[46:49], v[164:167], v[180:183], v[46:49]
	v_mfma_f32_16x16x32_bf16 v[42:45], v[172:175], v[180:183], v[42:45]
	v_mfma_f32_16x16x32_bf16 v[30:33], v[164:167], v[188:191], v[30:33]
	v_mfma_f32_16x16x32_bf16 v[26:29], v[172:175], v[188:191], v[26:29]
	v_mfma_f32_16x16x32_bf16 v[14:17], v[164:167], v[196:199], v[14:17]
	v_mfma_f32_16x16x32_bf16 v[10:13], v[172:175], v[196:199], v[10:13]
	v_mfma_f32_16x16x32_bf16 v[6:9], v[164:167], v[204:207], v[6:9]
	v_mfma_f32_16x16x32_bf16 v[2:5], v[172:175], v[204:207], v[2:5]
	s_barrier
	s_setprio 0
	s_add_i32 s53, s53, 2
	s_add_u32 s16, s16, 0x100
	s_addc_u32 s17, s17, 0
	s_add_u32 s51, s51, 0x100
	s_addc_u32 s52, s52, 0
	s_cmp_gt_u32 s53, 29
	s_cbranch_scc1 .Lpeel_done_0

.LBB0_1562:
	v_add_u32_e32 v158, 0x10000, v160
	ds_read_b128 v[164:167], v158
	ds_read_b128 v[168:171], v158 offset:1024
	ds_read_b128 v[172:175], v158 offset:2048
	ds_read_b128 v[176:179], v158 offset:3072
	v_add_u32_e32 v158, 0x14000, v160
	ds_read_b128 v[180:183], v158
	ds_read_b128 v[184:187], v158 offset:1024
	ds_read_b128 v[188:191], v158 offset:2048
	ds_read_b128 v[192:195], v158 offset:3072
	ds_read_b128 v[196:199], v162
	ds_read_b128 v[200:203], v162 offset:1024
	ds_read_b128 v[204:207], v162 offset:2048
	ds_read_b128 v[220:223], v162 offset:3072
	ds_read_b128 v[224:227], v162 offset:4096
	ds_read_b128 v[228:231], v162 offset:5120
	ds_read_b128 v[232:235], v162 offset:6144
	ds_read_b128 v[236:239], v162 offset:7168
	s_add_i32 s49, s49, 1
	s_mul_i32 s7, s49, s48
	s_mul_hi_u32 s9, s49, s25
	s_add_i32 s9, s9, s7
	s_mul_i32 s7, s49, s25
	s_add_u32 s10, s7, s36
	s_addc_u32 s11, s9, s42
	v_mov_b64_e32 v[2:3], s[68:69]
	v_cmp_ge_i64_e32 vcc, s[10:11], v[2:3]
	v_cmp_lt_i64_e64 s[34:35], s[10:11], v[2:3]
	s_cbranch_vccnz .LBB0_1564
	s_ashr_i32 s6, s10, 31
	s_lshr_b32 s6, s6, 29
	s_add_i32 s6, s10, s6
	s_ashr_i32 s7, s6, 3
	s_and_b32 s6, s6, -8
	s_sub_i32 s6, s10, s6
	s_cmp_lt_i32 s6, 0
	s_cselect_b32 s8, s40, s39
	s_mul_i32 s6, s8, s6
	s_add_i32 s6, s6, s7
	s_mul_hi_i32 s7, s6, 0x2e8ba2e9
	s_lshr_b32 s8, s7, 31
	s_ashr_i32 s7, s7, 6
	s_add_i32 s7, s7, s8
	s_lshl_b32 s8, s7, 3
	s_sub_i32 s9, s24, s8
	s_min_i32 s9, s9, 8
	s_abs_i32 s10, s9
	v_cvt_f32_u32_e32 v2, s10
	s_sub_i32 s12, 0, s10
	s_mulk_i32 s7, 0x160
	s_sub_i32 s7, s6, s7
	v_rcp_iflag_f32_e32 v2, v2
	s_abs_i32 s6, s7
	s_xor_b32 s11, s7, s9
	s_ashr_i32 s11, s11, 31
	v_mul_f32_e32 v2, 0x4f7ffffe, v2
	v_cvt_u32_f32_e32 v2, v2
	s_nop 0
	v_readfirstlane_b32 s13, v2
	s_mul_i32 s12, s12, s13
	s_mul_hi_u32 s12, s13, s12
	s_add_i32 s13, s13, s12
	s_mul_hi_u32 s12, s6, s13
	s_mul_i32 s13, s12, s10
	s_sub_i32 s6, s6, s13
	s_add_i32 s15, s12, 1
	s_sub_i32 s13, s6, s10
	s_cmp_ge_u32 s6, s10
	s_cselect_b32 s12, s15, s12
	s_cselect_b32 s6, s13, s6
	s_add_i32 s13, s12, 1
	s_cmp_ge_u32 s6, s10
	s_cselect_b32 s6, s13, s12
	s_xor_b32 s6, s6, s11
	s_sub_i32 s6, s6, s11
	s_mul_i32 s9, s6, s9
	s_sub_i32 s7, s7, s9
	s_add_i32 s8, s7, s8
.LBB0_1564:
	s_ashr_i32 s9, s8, 31
	s_lshl_b64 s[10:11], s[8:9], 20
	v_readlane_b32 s12, v253, 25
	v_readlane_b32 s13, v253, 26
	s_add_u32 s10, s12, s10
	s_addc_u32 s11, s13, s11
	s_and_b64 s[12:13], s[34:35], exec
	s_cselect_b32 s9, s11, s19
	s_cselect_b32 s15, s10, s18
	s_ashr_i32 s7, s6, 31
	s_lshl_b64 s[12:13], s[6:7], 20
	s_add_u32 s12, s37, s12
	s_addc_u32 s13, s38, s13
	s_and_b64 s[22:23], s[34:35], exec
	s_cselect_b32 s7, s13, s21
	s_cselect_b32 s50, s12, s20
	s_add_u32 s18, s18, 0x80080
	s_addc_u32 s19, s19, 0
	s_add_u32 s51, s20, 0x100
	s_addc_u32 s52, s21, 0
	s_mov_b32 s53, -2
	s_add_u32 s20, s18, 0xfff80080
	s_addc_u32 s21, s19, -1
	s_add_i32 s54, 0, 0x10000
	s_cmp_eq_u32 s53, 28
	s_cselect_b32 s23, s9, s21
	s_cselect_b32 s22, s15, s20
	s_cselect_b32 s21, s7, s52
	s_cselect_b32 s20, s50, s51
	s_add_i32 s56, 0, 0x14000
	v_lshl_add_u64 v[158:159], s[18:19], 0, v[154:155]
	s_add_i32 m0, s17, 0xc000
	global_load_lds_dwordx4 v[158:159], off
	v_lshl_add_u64 v[158:159], s[18:19], 0, v[156:157]
	s_add_i32 m0, s17, 0xe000
	s_nop 0
	global_load_lds_dwordx4 v[158:159], off
	s_waitcnt vmcnt(8)
	s_waitcnt lgkmcnt(0)
	s_setprio 1
	s_barrier
	v_mfma_f32_16x16x32_bf16 v[122:125], v[164:167], v[196:199], 0
	v_mfma_f32_16x16x32_bf16 v[114:117], v[172:175], v[196:199], 0
	v_mfma_f32_16x16x32_bf16 v[106:109], v[164:167], v[204:207], 0
	v_mfma_f32_16x16x32_bf16 v[98:101], v[172:175], v[204:207], 0
	v_mfma_f32_16x16x32_bf16 v[90:93], v[164:167], v[224:227], 0
	v_mfma_f32_16x16x32_bf16 v[82:85], v[172:175], v[224:227], 0
	v_mfma_f32_16x16x32_bf16 v[74:77], v[164:167], v[232:235], 0
	v_mfma_f32_16x16x32_bf16 v[66:69], v[172:175], v[232:235], 0
	v_mfma_f32_16x16x32_bf16 v[122:125], v[168:171], v[200:203], v[122:125]
	v_mfma_f32_16x16x32_bf16 v[114:117], v[176:179], v[200:203], v[114:117]
	v_mfma_f32_16x16x32_bf16 v[106:109], v[168:171], v[220:223], v[106:109]
	v_mfma_f32_16x16x32_bf16 v[98:101], v[176:179], v[220:223], v[98:101]
	v_mfma_f32_16x16x32_bf16 v[90:93], v[168:171], v[228:231], v[90:93]
	v_mfma_f32_16x16x32_bf16 v[82:85], v[176:179], v[228:231], v[82:85]
	v_mfma_f32_16x16x32_bf16 v[74:77], v[168:171], v[236:239], v[74:77]
	v_mfma_f32_16x16x32_bf16 v[66:69], v[176:179], v[236:239], v[66:69]
	s_setprio 0
	s_setprio 1
	v_mfma_f32_16x16x32_bf16 v[126:129], v[180:183], v[196:199], 0
	v_mfma_f32_16x16x32_bf16 v[118:121], v[188:191], v[196:199], 0
	v_mfma_f32_16x16x32_bf16 v[110:113], v[180:183], v[204:207], 0
	v_mfma_f32_16x16x32_bf16 v[102:105], v[188:191], v[204:207], 0
	v_mfma_f32_16x16x32_bf16 v[94:97], v[180:183], v[224:227], 0
	v_mfma_f32_16x16x32_bf16 v[86:89], v[188:191], v[224:227], 0
	v_mfma_f32_16x16x32_bf16 v[78:81], v[180:183], v[232:235], 0
	v_mfma_f32_16x16x32_bf16 v[70:73], v[188:191], v[232:235], 0
	v_mfma_f32_16x16x32_bf16 v[126:129], v[184:187], v[200:203], v[126:129]
	v_mfma_f32_16x16x32_bf16 v[118:121], v[192:195], v[200:203], v[118:121]
	v_mfma_f32_16x16x32_bf16 v[110:113], v[184:187], v[220:223], v[110:113]
	v_mfma_f32_16x16x32_bf16 v[102:105], v[192:195], v[220:223], v[102:105]
	v_mfma_f32_16x16x32_bf16 v[94:97], v[184:187], v[228:231], v[94:97]
	v_mfma_f32_16x16x32_bf16 v[86:89], v[192:195], v[228:231], v[86:89]
	v_mfma_f32_16x16x32_bf16 v[78:81], v[184:187], v[236:239], v[78:81]
	v_mfma_f32_16x16x32_bf16 v[70:73], v[192:195], v[236:239], v[70:73]
	s_barrier
	s_setprio 0
	s_add_i32 s54, s54, s41
	v_lshl_add_u64 v[158:159], s[20:21], 0, v[0:1]
	s_mov_b32 m0, s54
	ds_read_b128 v[196:199], v162 offset:16384
	ds_read_b128 v[200:203], v162 offset:17408
	ds_read_b128 v[204:207], v162 offset:18432
	ds_read_b128 v[220:223], v162 offset:19456
	ds_read_b128 v[224:227], v162 offset:20480
	ds_read_b128 v[228:231], v162 offset:21504
	ds_read_b128 v[232:235], v162 offset:22528
	ds_read_b128 v[236:239], v162 offset:23552
	global_load_lds_dwordx4 v[158:159], off
	s_add_i32 m0, s54, 0x2000
	s_add_u32 s54, s20, 0x80000
	v_lshl_add_u64 v[208:209], s[20:21], 0, v[130:131]
	s_addc_u32 s55, s21, 0
	s_add_i32 s56, s56, s41
	global_load_lds_dwordx4 v[208:209], off
	v_lshl_add_u64 v[216:217], s[54:55], 0, v[0:1]
	s_mov_b32 m0, s56
	v_lshl_add_u64 v[244:245], s[22:23], 0, v[132:133]
	global_load_lds_dwordx4 v[216:217], off
	v_lshl_add_u64 v[216:217], s[54:55], 0, v[130:131]
	s_add_i32 m0, s56, 0x2000
	s_nop 0
	global_load_lds_dwordx4 v[216:217], off
	v_lshl_add_u64 v[216:217], s[22:23], 0, v[134:135]
	s_mov_b32 m0, s17
	s_nop 0
	global_load_lds_dwordx4 v[216:217], off
	s_mov_b32 m0, s43
	s_nop 0
	global_load_lds_dwordx4 v[244:245], off
	s_waitcnt vmcnt(8)
	s_waitcnt lgkmcnt(0)
	s_setprio 1
	s_barrier
	v_mfma_f32_16x16x32_bf16 v[58:61], v[164:167], v[196:199], 0
	v_mfma_f32_16x16x32_bf16 v[50:53], v[172:175], v[196:199], 0
	v_mfma_f32_16x16x32_bf16 v[42:45], v[164:167], v[204:207], 0
	v_mfma_f32_16x16x32_bf16 v[34:37], v[172:175], v[204:207], 0
	v_mfma_f32_16x16x32_bf16 v[26:29], v[164:167], v[224:227], 0
	v_mfma_f32_16x16x32_bf16 v[18:21], v[172:175], v[224:227], 0
	v_mfma_f32_16x16x32_bf16 v[10:13], v[164:167], v[232:235], 0
	v_mfma_f32_16x16x32_bf16 v[2:5], v[172:175], v[232:235], 0
	v_mfma_f32_16x16x32_bf16 v[58:61], v[168:171], v[200:203], v[58:61]
	v_mfma_f32_16x16x32_bf16 v[50:53], v[176:179], v[200:203], v[50:53]
	v_mfma_f32_16x16x32_bf16 v[42:45], v[168:171], v[220:223], v[42:45]
	v_mfma_f32_16x16x32_bf16 v[34:37], v[176:179], v[220:223], v[34:37]
	v_mfma_f32_16x16x32_bf16 v[26:29], v[168:171], v[228:231], v[26:29]
	v_mfma_f32_16x16x32_bf16 v[18:21], v[176:179], v[228:231], v[18:21]
	v_mfma_f32_16x16x32_bf16 v[10:13], v[168:171], v[236:239], v[10:13]
	v_mfma_f32_16x16x32_bf16 v[2:5], v[176:179], v[236:239], v[2:5]
	s_setprio 0
	s_setprio 1
	v_mfma_f32_16x16x32_bf16 v[62:65], v[180:183], v[196:199], 0
	v_mfma_f32_16x16x32_bf16 v[54:57], v[188:191], v[196:199], 0
	v_mfma_f32_16x16x32_bf16 v[46:49], v[180:183], v[204:207], 0
	v_mfma_f32_16x16x32_bf16 v[38:41], v[188:191], v[204:207], 0
	v_mfma_f32_16x16x32_bf16 v[30:33], v[180:183], v[224:227], 0
	v_mfma_f32_16x16x32_bf16 v[22:25], v[188:191], v[224:227], 0
	v_mfma_f32_16x16x32_bf16 v[14:17], v[180:183], v[232:235], 0
	v_mfma_f32_16x16x32_bf16 v[6:9], v[188:191], v[232:235], 0
	v_mfma_f32_16x16x32_bf16 v[62:65], v[184:187], v[200:203], v[62:65]
	v_mfma_f32_16x16x32_bf16 v[54:57], v[192:195], v[200:203], v[54:57]
	v_mfma_f32_16x16x32_bf16 v[46:49], v[184:187], v[220:223], v[46:49]
	v_mfma_f32_16x16x32_bf16 v[38:41], v[192:195], v[220:223], v[38:41]
	v_mfma_f32_16x16x32_bf16 v[30:33], v[184:187], v[228:231], v[30:33]
	v_mfma_f32_16x16x32_bf16 v[22:25], v[192:195], v[228:231], v[22:25]
	v_mfma_f32_16x16x32_bf16 v[14:17], v[184:187], v[236:239], v[14:17]
	v_mfma_f32_16x16x32_bf16 v[6:9], v[192:195], v[236:239], v[6:9]
	s_barrier
	s_setprio 0
	s_add_i32 s54, 0, 0x18000
	v_add_u32_e32 v163, s54, v160
	s_add_i32 s55, 0, 0x1c000
	ds_read_b128 v[164:167], v163
	ds_read_b128 v[168:171], v163 offset:1024
	ds_read_b128 v[172:175], v163 offset:2048
	ds_read_b128 v[176:179], v163 offset:3072
	v_add_u32_e32 v163, s55, v160
	ds_read_b128 v[180:183], v163
	ds_read_b128 v[184:187], v163 offset:1024
	ds_read_b128 v[188:191], v163 offset:2048
	ds_read_b128 v[192:195], v163 offset:3072
	s_add_u32 s22, s22, 0x80000
	s_addc_u32 s23, s23, 0
	s_mov_b32 m0, s44
	v_lshl_add_u64 v[246:247], s[22:23], 0, v[134:135]
	ds_read_b128 v[196:199], v162 offset:32768
	ds_read_b128 v[200:203], v162 offset:33792
	ds_read_b128 v[204:207], v162 offset:34816
	ds_read_b128 v[220:223], v162 offset:35840
	ds_read_b128 v[224:227], v162 offset:36864
	ds_read_b128 v[228:231], v162 offset:37888
	ds_read_b128 v[232:235], v162 offset:38912
	ds_read_b128 v[236:239], v162 offset:39936
	global_load_lds_dwordx4 v[246:247], off
	v_lshl_add_u64 v[246:247], s[22:23], 0, v[132:133]
	s_mov_b32 m0, s45
	s_nop 0
	global_load_lds_dwordx4 v[246:247], off
	s_waitcnt vmcnt(8)
	s_waitcnt lgkmcnt(0)
	s_setprio 1
	s_barrier
	v_mfma_f32_16x16x32_bf16 v[122:125], v[164:167], v[196:199], v[122:125]
	v_mfma_f32_16x16x32_bf16 v[114:117], v[172:175], v[196:199], v[114:117]
	v_mfma_f32_16x16x32_bf16 v[106:109], v[164:167], v[204:207], v[106:109]
	v_mfma_f32_16x16x32_bf16 v[98:101], v[172:175], v[204:207], v[98:101]
	v_mfma_f32_16x16x32_bf16 v[90:93], v[164:167], v[224:227], v[90:93]
	v_mfma_f32_16x16x32_bf16 v[82:85], v[172:175], v[224:227], v[82:85]
	v_mfma_f32_16x16x32_bf16 v[74:77], v[164:167], v[232:235], v[74:77]
	v_mfma_f32_16x16x32_bf16 v[66:69], v[172:175], v[232:235], v[66:69]
	v_mfma_f32_16x16x32_bf16 v[122:125], v[168:171], v[200:203], v[122:125]
	v_mfma_f32_16x16x32_bf16 v[114:117], v[176:179], v[200:203], v[114:117]
	v_mfma_f32_16x16x32_bf16 v[106:109], v[168:171], v[220:223], v[106:109]
	v_mfma_f32_16x16x32_bf16 v[98:101], v[176:179], v[220:223], v[98:101]
	v_mfma_f32_16x16x32_bf16 v[90:93], v[168:171], v[228:231], v[90:93]
	v_mfma_f32_16x16x32_bf16 v[82:85], v[176:179], v[228:231], v[82:85]
	v_mfma_f32_16x16x32_bf16 v[74:77], v[168:171], v[236:239], v[74:77]
	v_mfma_f32_16x16x32_bf16 v[66:69], v[176:179], v[236:239], v[66:69]
	s_setprio 0
	s_setprio 1
	v_mfma_f32_16x16x32_bf16 v[126:129], v[180:183], v[196:199], v[126:129]
	v_mfma_f32_16x16x32_bf16 v[118:121], v[188:191], v[196:199], v[118:121]
	v_mfma_f32_16x16x32_bf16 v[110:113], v[180:183], v[204:207], v[110:113]
	v_mfma_f32_16x16x32_bf16 v[102:105], v[188:191], v[204:207], v[102:105]
	v_mfma_f32_16x16x32_bf16 v[94:97], v[180:183], v[224:227], v[94:97]
	v_mfma_f32_16x16x32_bf16 v[86:89], v[188:191], v[224:227], v[86:89]
	v_mfma_f32_16x16x32_bf16 v[78:81], v[180:183], v[232:235], v[78:81]
	v_mfma_f32_16x16x32_bf16 v[70:73], v[188:191], v[232:235], v[70:73]
	v_mfma_f32_16x16x32_bf16 v[126:129], v[184:187], v[200:203], v[126:129]
	v_mfma_f32_16x16x32_bf16 v[118:121], v[192:195], v[200:203], v[118:121]
	v_mfma_f32_16x16x32_bf16 v[110:113], v[184:187], v[220:223], v[110:113]
	v_mfma_f32_16x16x32_bf16 v[102:105], v[192:195], v[220:223], v[102:105]
	v_mfma_f32_16x16x32_bf16 v[94:97], v[184:187], v[228:231], v[94:97]
	v_mfma_f32_16x16x32_bf16 v[86:89], v[192:195], v[228:231], v[86:89]
	v_mfma_f32_16x16x32_bf16 v[78:81], v[184:187], v[236:239], v[78:81]
	v_mfma_f32_16x16x32_bf16 v[70:73], v[192:195], v[236:239], v[70:73]
	s_barrier
	s_setprio 0
	s_add_i32 s22, s54, s41
	v_lshl_add_u64 v[158:159], v[158:159], 0, s[2:3]
	s_mov_b32 m0, s22
	ds_read_b128 v[196:199], v162 offset:49152
	ds_read_b128 v[200:203], v162 offset:50176
	ds_read_b128 v[204:207], v162 offset:51200
	ds_read_b128 v[220:223], v162 offset:52224
	ds_read_b128 v[224:227], v162 offset:53248
	ds_read_b128 v[228:231], v162 offset:54272
	ds_read_b128 v[232:235], v162 offset:55296
	ds_read_b128 v[236:239], v162 offset:56320
	global_load_lds_dwordx4 v[158:159], off
	s_add_i32 m0, s22, 0x2000
	s_add_u32 s20, s20, 0x80080
	v_lshl_add_u64 v[158:159], v[208:209], 0, s[2:3]
	s_addc_u32 s21, s21, 0
	s_add_i32 s22, s55, s41
	global_load_lds_dwordx4 v[158:159], off
	v_lshl_add_u64 v[158:159], s[20:21], 0, v[0:1]
	s_mov_b32 m0, s22
	s_nop 0
	global_load_lds_dwordx4 v[158:159], off
	v_lshl_add_u64 v[158:159], s[20:21], 0, v[130:131]
	s_add_i32 m0, s22, 0x2000
	s_nop 0
	global_load_lds_dwordx4 v[158:159], off
	v_lshl_add_u64 v[158:159], v[216:217], 0, s[2:3]
	s_mov_b32 m0, s46
	s_nop 0
	global_load_lds_dwordx4 v[158:159], off
	v_lshl_add_u64 v[158:159], v[244:245], 0, s[2:3]
	s_mov_b32 m0, s47
	s_nop 0
	global_load_lds_dwordx4 v[158:159], off
	s_waitcnt vmcnt(8)
	s_waitcnt lgkmcnt(0)
	s_setprio 1
	s_barrier
	v_mfma_f32_16x16x32_bf16 v[58:61], v[164:167], v[196:199], v[58:61]
	v_mfma_f32_16x16x32_bf16 v[50:53], v[172:175], v[196:199], v[50:53]
	v_mfma_f32_16x16x32_bf16 v[42:45], v[164:167], v[204:207], v[42:45]
	v_mfma_f32_16x16x32_bf16 v[34:37], v[172:175], v[204:207], v[34:37]
	v_mfma_f32_16x16x32_bf16 v[26:29], v[164:167], v[224:227], v[26:29]
	v_mfma_f32_16x16x32_bf16 v[18:21], v[172:175], v[224:227], v[18:21]
	v_mfma_f32_16x16x32_bf16 v[10:13], v[164:167], v[232:235], v[10:13]
	v_mfma_f32_16x16x32_bf16 v[2:5], v[172:175], v[232:235], v[2:5]
	v_mfma_f32_16x16x32_bf16 v[58:61], v[168:171], v[200:203], v[58:61]
	v_mfma_f32_16x16x32_bf16 v[50:53], v[176:179], v[200:203], v[50:53]
	v_mfma_f32_16x16x32_bf16 v[42:45], v[168:171], v[220:223], v[42:45]
	v_mfma_f32_16x16x32_bf16 v[34:37], v[176:179], v[220:223], v[34:37]
	v_mfma_f32_16x16x32_bf16 v[26:29], v[168:171], v[228:231], v[26:29]
	v_mfma_f32_16x16x32_bf16 v[18:21], v[176:179], v[228:231], v[18:21]
	v_mfma_f32_16x16x32_bf16 v[10:13], v[168:171], v[236:239], v[10:13]
	v_mfma_f32_16x16x32_bf16 v[2:5], v[176:179], v[236:239], v[2:5]
	s_setprio 0
	s_setprio 1
	v_mfma_f32_16x16x32_bf16 v[62:65], v[180:183], v[196:199], v[62:65]
	v_mfma_f32_16x16x32_bf16 v[54:57], v[188:191], v[196:199], v[54:57]
	v_mfma_f32_16x16x32_bf16 v[46:49], v[180:183], v[204:207], v[46:49]
	v_mfma_f32_16x16x32_bf16 v[38:41], v[188:191], v[204:207], v[38:41]
	v_mfma_f32_16x16x32_bf16 v[30:33], v[180:183], v[224:227], v[30:33]
	v_mfma_f32_16x16x32_bf16 v[22:25], v[188:191], v[224:227], v[22:25]
	v_mfma_f32_16x16x32_bf16 v[14:17], v[180:183], v[232:235], v[14:17]
	v_mfma_f32_16x16x32_bf16 v[6:9], v[188:191], v[232:235], v[6:9]
	v_mfma_f32_16x16x32_bf16 v[62:65], v[184:187], v[200:203], v[62:65]
	v_mfma_f32_16x16x32_bf16 v[54:57], v[192:195], v[200:203], v[54:57]
	v_mfma_f32_16x16x32_bf16 v[46:49], v[184:187], v[220:223], v[46:49]
	v_mfma_f32_16x16x32_bf16 v[38:41], v[192:195], v[220:223], v[38:41]
	v_mfma_f32_16x16x32_bf16 v[30:33], v[184:187], v[228:231], v[30:33]
	v_mfma_f32_16x16x32_bf16 v[22:25], v[192:195], v[228:231], v[22:25]
	v_mfma_f32_16x16x32_bf16 v[14:17], v[184:187], v[236:239], v[14:17]
	v_mfma_f32_16x16x32_bf16 v[6:9], v[192:195], v[236:239], v[6:9]
	s_barrier
	s_setprio 0
	s_add_i32 s53, s53, 2
	s_add_u32 s18, s18, 0x100
	s_addc_u32 s19, s19, 0
	s_add_u32 s51, s51, 0x100
	s_addc_u32 s52, s52, 0
	s_cmp_gt_u32 s53, 29
	s_cbranch_scc1 .Lpeel_done_4
